# GEMM-2 nc loop replaced by streaming hand-written LDS-DMA GEMM with pipelined x-residual epilogue
# speedup vs baseline: 1.0117x; 1.0014x over previous
.Lg2_entry:
	v_and_b32_e32 v200, 63, v208
	v_lshrrev_b32_e32 v201, 6, v208
	v_lshrrev_b32_e32 v202, 3, v200
	v_and_b32_e32 v203, 7, v200
	v_xor_b32_e32 v203, v203, v202
	v_lshlrev_b32_e32 v203, 4, v203
	v_lshl_add_u32 v204, v201, 5, v202
	v_lshl_add_u32 v234, v204, 11, v203
	v_add_u32_e32 v235, 0x4000, v234
	v_add_u32_e32 v236, 0x8000, v234
	v_add_u32_e32 v237, 0xc000, v234
	v_lshlrev_b32_e32 v238, 4, v200
	v_add_u32_e32 v239, 0x8000, v238
	v_add_u32_e32 v240, 0x10000, v238
	v_add_u32_e32 v241, 0x18000, v238
	v_readfirstlane_b32 s8, v201
	s_lshl_b32 s60, s8, 12
	v_and_b32_e32 v200, 63, v208
	v_and_b32_e32 v205, 15, v200
	v_lshrrev_b32_e32 v206, 4, v200
	v_and_b32_e32 v207, 7, v205
	v_xor_b32_e32 v207, v207, v206
	v_lshlrev_b32_e32 v207, 4, v207
	v_lshl_add_u32 v242, v205, 7, v207
	v_xor_b32_e32 v243, 64, v242
	v_mov_b32_e32 v246, 0
	v_mov_b32_e32 v247, 0
	v_mov_b32_e32 v248, 0
	v_mov_b32_e32 v249, 0
	v_mov_b32_e32 v250, 0
	v_mov_b32_e32 v251, 0
	v_mov_b32_e32 v252, 0
	v_mov_b32_e32 v253, 0
	v_readlane_b32 s62, v254, 0
	v_readlane_b32 s63, v254, 1
	s_mov_b32 s21, 0
	s_lshl_b32 s8, s20, 18
	s_add_u32 s52, s92, s8
	s_addc_u32 s53, s93, 0
	s_lshl_b32 s8, s21, 19
	s_lshl_b32 s24, s60, 5
	s_add_i32 s8, s8, s24
	s_add_i32 s8, s8, 0x34600000
	s_add_u32 s54, s92, s8
	s_addc_u32 s55, s93, 0
	s_mov_b32 s59, 0
	s_mov_b32 s57, 0
	s_add_i32 m0, s57, s60
	s_nop 0
	global_load_lds_dwordx4 v234, s[52:53]
	s_add_i32 m0, m0, 0x400
	s_nop 0
	global_load_lds_dwordx4 v235, s[52:53]
	s_add_i32 m0, m0, 0x400
	s_nop 0
	global_load_lds_dwordx4 v236, s[52:53]
	s_add_i32 m0, m0, 0x400
	s_nop 0
	global_load_lds_dwordx4 v237, s[52:53]
	s_add_u32 s52, s52, 128
	s_addc_u32 s53, s53, 0
	global_load_dwordx4 v[128:131], v238, s[54:55]
	global_load_dwordx4 v[132:135], v239, s[54:55]
	global_load_dwordx4 v[136:139], v240, s[54:55]
	global_load_dwordx4 v[140:143], v241, s[54:55]
	s_add_u32 s54, s54, 1024
	s_addc_u32 s55, s55, 0
	s_add_i32 s59, s59, 1
	global_load_dwordx4 v[144:147], v238, s[54:55]
	global_load_dwordx4 v[148:151], v239, s[54:55]
	global_load_dwordx4 v[152:155], v240, s[54:55]
	global_load_dwordx4 v[156:159], v241, s[54:55]
	s_add_u32 s54, s54, 1024
	s_addc_u32 s55, s55, 0
	s_add_i32 s59, s59, 1
	s_movk_i32 s57, 0x4000
	s_add_i32 m0, s57, s60
	s_nop 0
	global_load_lds_dwordx4 v234, s[52:53]
	s_add_i32 m0, m0, 0x400
	s_nop 0
	global_load_lds_dwordx4 v235, s[52:53]
	s_add_i32 m0, m0, 0x400
	s_nop 0
	global_load_lds_dwordx4 v236, s[52:53]
	s_add_i32 m0, m0, 0x400
	s_nop 0
	global_load_lds_dwordx4 v237, s[52:53]
	s_add_u32 s52, s52, 128
	s_addc_u32 s53, s53, 0
	global_load_dwordx4 v[160:163], v238, s[54:55]
	global_load_dwordx4 v[164:167], v239, s[54:55]
	global_load_dwordx4 v[168:171], v240, s[54:55]
	global_load_dwordx4 v[172:175], v241, s[54:55]
	s_add_u32 s54, s54, 1024
	s_addc_u32 s55, s55, 0
	s_add_i32 s59, s59, 1
	s_mov_b32 s56, 0
	s_mov_b32 s57, 0x8000
.Lg2_chunk:
	v_mov_b32_e32 v0, 0
	v_mov_b32_e32 v1, 0
	v_mov_b32_e32 v2, 0
	v_mov_b32_e32 v3, 0
	v_mov_b32_e32 v4, 0
	v_mov_b32_e32 v5, 0
	v_mov_b32_e32 v6, 0
	v_mov_b32_e32 v7, 0
	v_mov_b32_e32 v8, 0
	v_mov_b32_e32 v9, 0
	v_mov_b32_e32 v10, 0
	v_mov_b32_e32 v11, 0
	v_mov_b32_e32 v12, 0
	v_mov_b32_e32 v13, 0
	v_mov_b32_e32 v14, 0
	v_mov_b32_e32 v15, 0
	v_mov_b32_e32 v16, 0
	v_mov_b32_e32 v17, 0
	v_mov_b32_e32 v18, 0
	v_mov_b32_e32 v19, 0
	v_mov_b32_e32 v20, 0
	v_mov_b32_e32 v21, 0
	v_mov_b32_e32 v22, 0
	v_mov_b32_e32 v23, 0
	v_mov_b32_e32 v24, 0
	v_mov_b32_e32 v25, 0
	v_mov_b32_e32 v26, 0
	v_mov_b32_e32 v27, 0
	v_mov_b32_e32 v28, 0
	v_mov_b32_e32 v29, 0
	v_mov_b32_e32 v30, 0
	v_mov_b32_e32 v31, 0
	v_mov_b32_e32 v32, 0
	v_mov_b32_e32 v33, 0
	v_mov_b32_e32 v34, 0
	v_mov_b32_e32 v35, 0
	v_mov_b32_e32 v36, 0
	v_mov_b32_e32 v37, 0
	v_mov_b32_e32 v38, 0
	v_mov_b32_e32 v39, 0
	v_mov_b32_e32 v40, 0
	v_mov_b32_e32 v41, 0
	v_mov_b32_e32 v42, 0
	v_mov_b32_e32 v43, 0
	v_mov_b32_e32 v44, 0
	v_mov_b32_e32 v45, 0
	v_mov_b32_e32 v46, 0
	v_mov_b32_e32 v47, 0
	v_mov_b32_e32 v48, 0
	v_mov_b32_e32 v49, 0
	v_mov_b32_e32 v50, 0
	v_mov_b32_e32 v51, 0
	v_mov_b32_e32 v52, 0
	v_mov_b32_e32 v53, 0
	v_mov_b32_e32 v54, 0
	v_mov_b32_e32 v55, 0
	v_mov_b32_e32 v56, 0
	v_mov_b32_e32 v57, 0
	v_mov_b32_e32 v58, 0
	v_mov_b32_e32 v59, 0
	v_mov_b32_e32 v60, 0
	v_mov_b32_e32 v61, 0
	v_mov_b32_e32 v62, 0
	v_mov_b32_e32 v63, 0
	v_mov_b32_e32 v64, 0
	v_mov_b32_e32 v65, 0
	v_mov_b32_e32 v66, 0
	v_mov_b32_e32 v67, 0
	v_mov_b32_e32 v68, 0
	v_mov_b32_e32 v69, 0
	v_mov_b32_e32 v70, 0
	v_mov_b32_e32 v71, 0
	v_mov_b32_e32 v72, 0
	v_mov_b32_e32 v73, 0
	v_mov_b32_e32 v74, 0
	v_mov_b32_e32 v75, 0
	v_mov_b32_e32 v76, 0
	v_mov_b32_e32 v77, 0
	v_mov_b32_e32 v78, 0
	v_mov_b32_e32 v79, 0
	v_mov_b32_e32 v80, 0
	v_mov_b32_e32 v81, 0
	v_mov_b32_e32 v82, 0
	v_mov_b32_e32 v83, 0
	v_mov_b32_e32 v84, 0
	v_mov_b32_e32 v85, 0
	v_mov_b32_e32 v86, 0
	v_mov_b32_e32 v87, 0
	v_mov_b32_e32 v88, 0
	v_mov_b32_e32 v89, 0
	v_mov_b32_e32 v90, 0
	v_mov_b32_e32 v91, 0
	v_mov_b32_e32 v92, 0
	v_mov_b32_e32 v93, 0
	v_mov_b32_e32 v94, 0
	v_mov_b32_e32 v95, 0
	v_mov_b32_e32 v96, 0
	v_mov_b32_e32 v97, 0
	v_mov_b32_e32 v98, 0
	v_mov_b32_e32 v99, 0
	v_mov_b32_e32 v100, 0
	v_mov_b32_e32 v101, 0
	v_mov_b32_e32 v102, 0
	v_mov_b32_e32 v103, 0
	v_mov_b32_e32 v104, 0
	v_mov_b32_e32 v105, 0
	v_mov_b32_e32 v106, 0
	v_mov_b32_e32 v107, 0
	v_mov_b32_e32 v108, 0
	v_mov_b32_e32 v109, 0
	v_mov_b32_e32 v110, 0
	v_mov_b32_e32 v111, 0
	v_mov_b32_e32 v112, 0
	v_mov_b32_e32 v113, 0
	v_mov_b32_e32 v114, 0
	v_mov_b32_e32 v115, 0
	v_mov_b32_e32 v116, 0
	v_mov_b32_e32 v117, 0
	v_mov_b32_e32 v118, 0
	v_mov_b32_e32 v119, 0
	v_mov_b32_e32 v120, 0
	v_mov_b32_e32 v121, 0
	v_mov_b32_e32 v122, 0
	v_mov_b32_e32 v123, 0
	v_mov_b32_e32 v124, 0
	v_mov_b32_e32 v125, 0
	v_mov_b32_e32 v126, 0
	v_mov_b32_e32 v127, 0
	s_mov_b32 s59, 3
	s_mov_b32 s58, 0
.Lg2_loop:
	s_waitcnt vmcnt(12)
	s_barrier
	global_load_dwordx4 v[176:179], v238, s[54:55]
	global_load_dwordx4 v[184:187], v239, s[54:55]
	global_load_dwordx4 v[188:191], v240, s[54:55]
	global_load_dwordx4 v[196:199], v241, s[54:55]
	s_cmp_eq_u32 s59, 31
	s_cbranch_scc1 .Lg2_sww0
	s_add_u32 s54, s54, 1024
	s_addc_u32 s55, s55, 0
	s_branch .Lg2_swdw0
.Lg2_sww0:
	s_cmp_lt_u32 s21, 3
	s_cbranch_scc0 .Lg2_wndw0
	s_add_i32 s25, s21, 1
	s_lshl_b32 s8, s25, 19
	s_lshl_b32 s24, s60, 5
	s_add_i32 s8, s8, s24
	s_add_i32 s8, s8, 0x34600000
	s_add_u32 s54, s92, s8
	s_addc_u32 s55, s93, 0
.Lg2_wndw0:
.Lg2_swdw0:
	s_add_i32 s59, s59, 1
	s_add_i32 m0, s57, s60
	s_nop 0
	global_load_lds_dwordx4 v234, s[52:53]
	s_add_i32 m0, m0, 0x400
	s_nop 0
	global_load_lds_dwordx4 v235, s[52:53]
	s_add_i32 m0, m0, 0x400
	s_nop 0
	global_load_lds_dwordx4 v236, s[52:53]
	s_add_i32 m0, m0, 0x400
	s_nop 0
	global_load_lds_dwordx4 v237, s[52:53]
	s_cmp_eq_u32 s58, 13
	s_cbranch_scc1 .Lg2_saa1
	s_add_u32 s52, s52, 128
	s_addc_u32 s53, s53, 0
	s_branch .Lg2_sada1
.Lg2_saa1:
	s_cmp_lt_u32 s21, 3
	s_cbranch_scc0 .Lg2_nda1
	s_lshl_b32 s8, s20, 18
	s_add_u32 s52, s92, s8
	s_addc_u32 s53, s93, 0
.Lg2_nda1:
.Lg2_sada1:
	v_add_u32_e32 v244, s56, v242
	v_add_u32_e32 v245, s56, v243
	ds_read_b128 v[200:203], v244 offset:0
	ds_read_b128 v[204:207], v244 offset:2048
	ds_read_b128 v[210:213], v244 offset:4096
	ds_read_b128 v[214:217], v244 offset:6144
	ds_read_b128 v[218:221], v244 offset:8192
	ds_read_b128 v[222:225], v244 offset:10240
	ds_read_b128 v[226:229], v244 offset:12288
	ds_read_b128 v[230:233], v244 offset:14336
	s_waitcnt lgkmcnt(4)
	v_mfma_f32_16x16x32_bf16 v[0:3], v[128:131], v[200:203], v[0:3]
	v_mfma_f32_16x16x32_bf16 v[32:35], v[132:135], v[200:203], v[32:35]
	v_mfma_f32_16x16x32_bf16 v[64:67], v[136:139], v[200:203], v[64:67]
	v_mfma_f32_16x16x32_bf16 v[96:99], v[140:143], v[200:203], v[96:99]
	v_mfma_f32_16x16x32_bf16 v[4:7], v[128:131], v[204:207], v[4:7]
	v_mfma_f32_16x16x32_bf16 v[36:39], v[132:135], v[204:207], v[36:39]
	v_mfma_f32_16x16x32_bf16 v[68:71], v[136:139], v[204:207], v[68:71]
	v_mfma_f32_16x16x32_bf16 v[100:103], v[140:143], v[204:207], v[100:103]
	v_mfma_f32_16x16x32_bf16 v[8:11], v[128:131], v[210:213], v[8:11]
	v_mfma_f32_16x16x32_bf16 v[40:43], v[132:135], v[210:213], v[40:43]
	v_mfma_f32_16x16x32_bf16 v[72:75], v[136:139], v[210:213], v[72:75]
	v_mfma_f32_16x16x32_bf16 v[104:107], v[140:143], v[210:213], v[104:107]
	v_mfma_f32_16x16x32_bf16 v[12:15], v[128:131], v[214:217], v[12:15]
	v_mfma_f32_16x16x32_bf16 v[44:47], v[132:135], v[214:217], v[44:47]
	v_mfma_f32_16x16x32_bf16 v[76:79], v[136:139], v[214:217], v[76:79]
	v_mfma_f32_16x16x32_bf16 v[108:111], v[140:143], v[214:217], v[108:111]
	s_waitcnt lgkmcnt(0)
	v_mfma_f32_16x16x32_bf16 v[16:19], v[128:131], v[218:221], v[16:19]
	v_mfma_f32_16x16x32_bf16 v[48:51], v[132:135], v[218:221], v[48:51]
	v_mfma_f32_16x16x32_bf16 v[80:83], v[136:139], v[218:221], v[80:83]
	v_mfma_f32_16x16x32_bf16 v[112:115], v[140:143], v[218:221], v[112:115]
	v_mfma_f32_16x16x32_bf16 v[20:23], v[128:131], v[222:225], v[20:23]
	v_mfma_f32_16x16x32_bf16 v[52:55], v[132:135], v[222:225], v[52:55]
	v_mfma_f32_16x16x32_bf16 v[84:87], v[136:139], v[222:225], v[84:87]
	v_mfma_f32_16x16x32_bf16 v[116:119], v[140:143], v[222:225], v[116:119]
	v_mfma_f32_16x16x32_bf16 v[24:27], v[128:131], v[226:229], v[24:27]
	v_mfma_f32_16x16x32_bf16 v[56:59], v[132:135], v[226:229], v[56:59]
	v_mfma_f32_16x16x32_bf16 v[88:91], v[136:139], v[226:229], v[88:91]
	v_mfma_f32_16x16x32_bf16 v[120:123], v[140:143], v[226:229], v[120:123]
	v_mfma_f32_16x16x32_bf16 v[28:31], v[128:131], v[230:233], v[28:31]
	v_mfma_f32_16x16x32_bf16 v[60:63], v[132:135], v[230:233], v[60:63]
	v_mfma_f32_16x16x32_bf16 v[92:95], v[136:139], v[230:233], v[92:95]
	v_mfma_f32_16x16x32_bf16 v[124:127], v[140:143], v[230:233], v[124:127]
	s_waitcnt vmcnt(16)
	global_load_dwordx4 v[128:131], v238, s[54:55]
	global_load_dwordx4 v[132:135], v239, s[54:55]
	global_load_dwordx4 v[136:139], v240, s[54:55]
	global_load_dwordx4 v[140:143], v241, s[54:55]
	s_cmp_eq_u32 s59, 31
	s_cbranch_scc1 .Lg2_sww2
	s_add_u32 s54, s54, 1024
	s_addc_u32 s55, s55, 0
	s_branch .Lg2_swdw2

.Lg2_wndw2:
.Lg2_swdw2:
	s_add_i32 s59, s59, 1
	ds_read_b128 v[200:203], v245 offset:0
	ds_read_b128 v[204:207], v245 offset:2048
	ds_read_b128 v[210:213], v245 offset:4096
	ds_read_b128 v[214:217], v245 offset:6144
	ds_read_b128 v[218:221], v245 offset:8192
	ds_read_b128 v[222:225], v245 offset:10240
	ds_read_b128 v[226:229], v245 offset:12288
	ds_read_b128 v[230:233], v245 offset:14336
	s_waitcnt lgkmcnt(4)
	v_mfma_f32_16x16x32_bf16 v[0:3], v[144:147], v[200:203], v[0:3]
	v_mfma_f32_16x16x32_bf16 v[32:35], v[148:151], v[200:203], v[32:35]
	v_mfma_f32_16x16x32_bf16 v[64:67], v[152:155], v[200:203], v[64:67]
	v_mfma_f32_16x16x32_bf16 v[96:99], v[156:159], v[200:203], v[96:99]
	v_mfma_f32_16x16x32_bf16 v[4:7], v[144:147], v[204:207], v[4:7]
	v_mfma_f32_16x16x32_bf16 v[36:39], v[148:151], v[204:207], v[36:39]
	v_mfma_f32_16x16x32_bf16 v[68:71], v[152:155], v[204:207], v[68:71]
	v_mfma_f32_16x16x32_bf16 v[100:103], v[156:159], v[204:207], v[100:103]
	v_mfma_f32_16x16x32_bf16 v[8:11], v[144:147], v[210:213], v[8:11]
	v_mfma_f32_16x16x32_bf16 v[40:43], v[148:151], v[210:213], v[40:43]
	v_mfma_f32_16x16x32_bf16 v[72:75], v[152:155], v[210:213], v[72:75]
	v_mfma_f32_16x16x32_bf16 v[104:107], v[156:159], v[210:213], v[104:107]
	v_mfma_f32_16x16x32_bf16 v[12:15], v[144:147], v[214:217], v[12:15]
	v_mfma_f32_16x16x32_bf16 v[44:47], v[148:151], v[214:217], v[44:47]
	v_mfma_f32_16x16x32_bf16 v[76:79], v[152:155], v[214:217], v[76:79]
	v_mfma_f32_16x16x32_bf16 v[108:111], v[156:159], v[214:217], v[108:111]
	s_waitcnt lgkmcnt(0)
	v_mfma_f32_16x16x32_bf16 v[16:19], v[144:147], v[218:221], v[16:19]
	v_mfma_f32_16x16x32_bf16 v[48:51], v[148:151], v[218:221], v[48:51]
	v_mfma_f32_16x16x32_bf16 v[80:83], v[152:155], v[218:221], v[80:83]
	v_mfma_f32_16x16x32_bf16 v[112:115], v[156:159], v[218:221], v[112:115]
	v_mfma_f32_16x16x32_bf16 v[20:23], v[144:147], v[222:225], v[20:23]
	v_mfma_f32_16x16x32_bf16 v[52:55], v[148:151], v[222:225], v[52:55]
	v_mfma_f32_16x16x32_bf16 v[84:87], v[152:155], v[222:225], v[84:87]
	v_mfma_f32_16x16x32_bf16 v[116:119], v[156:159], v[222:225], v[116:119]
	v_mfma_f32_16x16x32_bf16 v[24:27], v[144:147], v[226:229], v[24:27]
	v_mfma_f32_16x16x32_bf16 v[56:59], v[148:151], v[226:229], v[56:59]
	v_mfma_f32_16x16x32_bf16 v[88:91], v[152:155], v[226:229], v[88:91]
	v_mfma_f32_16x16x32_bf16 v[120:123], v[156:159], v[226:229], v[120:123]
	v_mfma_f32_16x16x32_bf16 v[28:31], v[144:147], v[230:233], v[28:31]
	v_mfma_f32_16x16x32_bf16 v[60:63], v[148:151], v[230:233], v[60:63]
	v_mfma_f32_16x16x32_bf16 v[92:95], v[152:155], v[230:233], v[92:95]
	v_mfma_f32_16x16x32_bf16 v[124:127], v[156:159], v[230:233], v[124:127]
	s_add_i32 s56, s56, 0x4000
	s_cmp_lt_u32 s56, 0xc000
	s_cselect_b32 s56, s56, 0
	s_add_i32 s57, s57, 0x4000
	s_cmp_lt_u32 s57, 0xc000
	s_cselect_b32 s57, s57, 0
	s_add_i32 s58, s58, 1
	s_waitcnt vmcnt(12)
	s_barrier
	global_load_dwordx4 v[144:147], v238, s[54:55]
	global_load_dwordx4 v[148:151], v239, s[54:55]
	global_load_dwordx4 v[152:155], v240, s[54:55]
	global_load_dwordx4 v[156:159], v241, s[54:55]
	s_cmp_eq_u32 s59, 31
	s_cbranch_scc1 .Lg2_sww3
	s_add_u32 s54, s54, 1024
	s_addc_u32 s55, s55, 0
	s_branch .Lg2_swdw3

.Lg2_nda4:
.Lg2_sada4:
	v_add_u32_e32 v244, s56, v242
	v_add_u32_e32 v245, s56, v243
	ds_read_b128 v[200:203], v244 offset:0
	ds_read_b128 v[204:207], v244 offset:2048
	ds_read_b128 v[210:213], v244 offset:4096
	ds_read_b128 v[214:217], v244 offset:6144
	ds_read_b128 v[218:221], v244 offset:8192
	ds_read_b128 v[222:225], v244 offset:10240
	ds_read_b128 v[226:229], v244 offset:12288
	ds_read_b128 v[230:233], v244 offset:14336
	s_waitcnt lgkmcnt(4)
	v_mfma_f32_16x16x32_bf16 v[0:3], v[160:163], v[200:203], v[0:3]
	v_mfma_f32_16x16x32_bf16 v[32:35], v[164:167], v[200:203], v[32:35]
	v_mfma_f32_16x16x32_bf16 v[64:67], v[168:171], v[200:203], v[64:67]
	v_mfma_f32_16x16x32_bf16 v[96:99], v[172:175], v[200:203], v[96:99]
	v_mfma_f32_16x16x32_bf16 v[4:7], v[160:163], v[204:207], v[4:7]
	v_mfma_f32_16x16x32_bf16 v[36:39], v[164:167], v[204:207], v[36:39]
	v_mfma_f32_16x16x32_bf16 v[68:71], v[168:171], v[204:207], v[68:71]
	v_mfma_f32_16x16x32_bf16 v[100:103], v[172:175], v[204:207], v[100:103]
	v_mfma_f32_16x16x32_bf16 v[8:11], v[160:163], v[210:213], v[8:11]
	v_mfma_f32_16x16x32_bf16 v[40:43], v[164:167], v[210:213], v[40:43]
	v_mfma_f32_16x16x32_bf16 v[72:75], v[168:171], v[210:213], v[72:75]
	v_mfma_f32_16x16x32_bf16 v[104:107], v[172:175], v[210:213], v[104:107]
	v_mfma_f32_16x16x32_bf16 v[12:15], v[160:163], v[214:217], v[12:15]
	v_mfma_f32_16x16x32_bf16 v[44:47], v[164:167], v[214:217], v[44:47]
	v_mfma_f32_16x16x32_bf16 v[76:79], v[168:171], v[214:217], v[76:79]
	v_mfma_f32_16x16x32_bf16 v[108:111], v[172:175], v[214:217], v[108:111]
	s_waitcnt lgkmcnt(0)
	v_mfma_f32_16x16x32_bf16 v[16:19], v[160:163], v[218:221], v[16:19]
	v_mfma_f32_16x16x32_bf16 v[48:51], v[164:167], v[218:221], v[48:51]
	v_mfma_f32_16x16x32_bf16 v[80:83], v[168:171], v[218:221], v[80:83]
	v_mfma_f32_16x16x32_bf16 v[112:115], v[172:175], v[218:221], v[112:115]
	v_mfma_f32_16x16x32_bf16 v[20:23], v[160:163], v[222:225], v[20:23]
	v_mfma_f32_16x16x32_bf16 v[52:55], v[164:167], v[222:225], v[52:55]
	v_mfma_f32_16x16x32_bf16 v[84:87], v[168:171], v[222:225], v[84:87]
	v_mfma_f32_16x16x32_bf16 v[116:119], v[172:175], v[222:225], v[116:119]
	v_mfma_f32_16x16x32_bf16 v[24:27], v[160:163], v[226:229], v[24:27]
	v_mfma_f32_16x16x32_bf16 v[56:59], v[164:167], v[226:229], v[56:59]
	v_mfma_f32_16x16x32_bf16 v[88:91], v[168:171], v[226:229], v[88:91]
	v_mfma_f32_16x16x32_bf16 v[120:123], v[172:175], v[226:229], v[120:123]
	v_mfma_f32_16x16x32_bf16 v[28:31], v[160:163], v[230:233], v[28:31]
	v_mfma_f32_16x16x32_bf16 v[60:63], v[164:167], v[230:233], v[60:63]
	v_mfma_f32_16x16x32_bf16 v[92:95], v[168:171], v[230:233], v[92:95]
	v_mfma_f32_16x16x32_bf16 v[124:127], v[172:175], v[230:233], v[124:127]
	s_waitcnt vmcnt(16)
	global_load_dwordx4 v[160:163], v238, s[54:55]
	global_load_dwordx4 v[164:167], v239, s[54:55]
	global_load_dwordx4 v[168:171], v240, s[54:55]
	global_load_dwordx4 v[172:175], v241, s[54:55]
	s_cmp_eq_u32 s59, 31
	s_cbranch_scc1 .Lg2_sww5
	s_add_u32 s54, s54, 1024
	s_addc_u32 s55, s55, 0
	s_branch .Lg2_swdw5

.Lg2_wndw5:
.Lg2_swdw5:
	s_add_i32 s59, s59, 1
	ds_read_b128 v[200:203], v245 offset:0
	ds_read_b128 v[204:207], v245 offset:2048
	ds_read_b128 v[210:213], v245 offset:4096
	ds_read_b128 v[214:217], v245 offset:6144
	ds_read_b128 v[218:221], v245 offset:8192
	ds_read_b128 v[222:225], v245 offset:10240
	ds_read_b128 v[226:229], v245 offset:12288
	ds_read_b128 v[230:233], v245 offset:14336
	s_waitcnt lgkmcnt(4)
	v_mfma_f32_16x16x32_bf16 v[0:3], v[176:179], v[200:203], v[0:3]
	v_mfma_f32_16x16x32_bf16 v[32:35], v[184:187], v[200:203], v[32:35]
	v_mfma_f32_16x16x32_bf16 v[64:67], v[188:191], v[200:203], v[64:67]
	v_mfma_f32_16x16x32_bf16 v[96:99], v[196:199], v[200:203], v[96:99]
	v_mfma_f32_16x16x32_bf16 v[4:7], v[176:179], v[204:207], v[4:7]
	v_mfma_f32_16x16x32_bf16 v[36:39], v[184:187], v[204:207], v[36:39]
	v_mfma_f32_16x16x32_bf16 v[68:71], v[188:191], v[204:207], v[68:71]
	v_mfma_f32_16x16x32_bf16 v[100:103], v[196:199], v[204:207], v[100:103]
	v_mfma_f32_16x16x32_bf16 v[8:11], v[176:179], v[210:213], v[8:11]
	v_mfma_f32_16x16x32_bf16 v[40:43], v[184:187], v[210:213], v[40:43]
	v_mfma_f32_16x16x32_bf16 v[72:75], v[188:191], v[210:213], v[72:75]
	v_mfma_f32_16x16x32_bf16 v[104:107], v[196:199], v[210:213], v[104:107]
	v_mfma_f32_16x16x32_bf16 v[12:15], v[176:179], v[214:217], v[12:15]
	v_mfma_f32_16x16x32_bf16 v[44:47], v[184:187], v[214:217], v[44:47]
	v_mfma_f32_16x16x32_bf16 v[76:79], v[188:191], v[214:217], v[76:79]
	v_mfma_f32_16x16x32_bf16 v[108:111], v[196:199], v[214:217], v[108:111]
	s_waitcnt lgkmcnt(0)
	v_mfma_f32_16x16x32_bf16 v[16:19], v[176:179], v[218:221], v[16:19]
	v_mfma_f32_16x16x32_bf16 v[48:51], v[184:187], v[218:221], v[48:51]
	v_mfma_f32_16x16x32_bf16 v[80:83], v[188:191], v[218:221], v[80:83]
	v_mfma_f32_16x16x32_bf16 v[112:115], v[196:199], v[218:221], v[112:115]
	v_mfma_f32_16x16x32_bf16 v[20:23], v[176:179], v[222:225], v[20:23]
	v_mfma_f32_16x16x32_bf16 v[52:55], v[184:187], v[222:225], v[52:55]
	v_mfma_f32_16x16x32_bf16 v[84:87], v[188:191], v[222:225], v[84:87]
	v_mfma_f32_16x16x32_bf16 v[116:119], v[196:199], v[222:225], v[116:119]
	v_mfma_f32_16x16x32_bf16 v[24:27], v[176:179], v[226:229], v[24:27]
	v_mfma_f32_16x16x32_bf16 v[56:59], v[184:187], v[226:229], v[56:59]
	v_mfma_f32_16x16x32_bf16 v[88:91], v[188:191], v[226:229], v[88:91]
	v_mfma_f32_16x16x32_bf16 v[120:123], v[196:199], v[226:229], v[120:123]
	v_mfma_f32_16x16x32_bf16 v[28:31], v[176:179], v[230:233], v[28:31]
	v_mfma_f32_16x16x32_bf16 v[60:63], v[184:187], v[230:233], v[60:63]
	v_mfma_f32_16x16x32_bf16 v[92:95], v[188:191], v[230:233], v[92:95]
	v_mfma_f32_16x16x32_bf16 v[124:127], v[196:199], v[230:233], v[124:127]
	s_add_i32 s56, s56, 0x4000
	s_cmp_lt_u32 s56, 0xc000
	s_cselect_b32 s56, s56, 0
	s_add_i32 s57, s57, 0x4000
	s_cmp_lt_u32 s57, 0xc000
	s_cselect_b32 s57, s57, 0
	s_add_i32 s58, s58, 1
	s_cmp_lt_u32 s58, 16
	s_cbranch_scc1 .Lg2_loop
	s_nop 7
	s_nop 7
	v_and_b32_e32 v200, 63, v208
	v_lshrrev_b32_e32 v201, 6, v208
	v_and_b32_e32 v202, 15, v200
	v_lshrrev_b32_e32 v203, 4, v200
	s_lshl_b32 s8, s20, 7
	s_lshl_b32 s24, s21, 8
	v_add_u32_e32 v204, s8, v202
	v_lshlrev_b32_e32 v205, 2, v203
	v_lshl_add_u32 v205, v201, 6, v205
	v_add_u32_e32 v205, s24, v205
	v_lshlrev_b32_e32 v206, 12, v204
	v_lshl_add_u32 v206, v205, 2, v206
	v_mov_b32_e32 v245, s63
	v_add_co_u32_e32 v244, vcc, s62, v206
	s_nop 1
	v_addc_co_u32_e32 v245, vcc, 0, v245, vcc
	v_lshlrev_b32_e32 v206, 11, v204
	v_lshl_add_u32 v206, v205, 1, v206
	v_add_u32_e32 v206, 0x1e000000, v206
	v_mov_b32_e32 v243, s93
	v_add_co_u32_e32 v242, vcc, s92, v206
	s_nop 1
	v_addc_co_u32_e32 v243, vcc, 0, v243, vcc
	global_load_dwordx4 v[200:203], v[244:245], off offset:0
	global_load_dwordx4 v[204:207], v[244:245], off offset:64
	global_load_dwordx4 v[210:213], v[244:245], off offset:128
	global_load_dwordx4 v[214:217], v[244:245], off offset:192
	v_add_co_u32_e32 v244, vcc, 0x10000, v244
	s_nop 1
	v_addc_co_u32_e32 v245, vcc, 0, v245, vcc
	global_load_dwordx4 v[218:221], v[244:245], off offset:0
	global_load_dwordx4 v[222:225], v[244:245], off offset:64
	global_load_dwordx4 v[226:229], v[244:245], off offset:128
	global_load_dwordx4 v[230:233], v[244:245], off offset:192
	v_add_co_u32_e32 v244, vcc, 0x10000, v244
	s_nop 1
	v_addc_co_u32_e32 v245, vcc, 0, v245, vcc
	s_waitcnt vmcnt(4)
	v_pk_add_f32 v[200:201], v[200:201], v[0:1]
	v_pk_add_f32 v[202:203], v[202:203], v[2:3]
	v_fmac_f32_e32 v246, v200, v200
	v_fmac_f32_e32 v246, v201, v201
	v_fmac_f32_e32 v246, v202, v202
	v_fmac_f32_e32 v246, v203, v203
	v_cvt_pk_bf16_f32 v200, v200, v201
	v_cvt_pk_bf16_f32 v201, v202, v203
	global_store_dwordx2 v[242:243], v[200:201], off offset:0
	v_pk_add_f32 v[204:205], v[204:205], v[32:33]
	v_pk_add_f32 v[206:207], v[206:207], v[34:35]
	v_fmac_f32_e32 v246, v204, v204
	v_fmac_f32_e32 v246, v205, v205
	v_fmac_f32_e32 v246, v206, v206
	v_fmac_f32_e32 v246, v207, v207
	v_cvt_pk_bf16_f32 v204, v204, v205
	v_cvt_pk_bf16_f32 v205, v206, v207
	global_store_dwordx2 v[242:243], v[204:205], off offset:32
	v_pk_add_f32 v[210:211], v[210:211], v[64:65]
	v_pk_add_f32 v[212:213], v[212:213], v[66:67]
	v_fmac_f32_e32 v246, v210, v210
	v_fmac_f32_e32 v246, v211, v211
	v_fmac_f32_e32 v246, v212, v212
	v_fmac_f32_e32 v246, v213, v213
	v_cvt_pk_bf16_f32 v210, v210, v211
	v_cvt_pk_bf16_f32 v211, v212, v213
	global_store_dwordx2 v[242:243], v[210:211], off offset:64
	v_pk_add_f32 v[214:215], v[214:215], v[96:97]
	v_pk_add_f32 v[216:217], v[216:217], v[98:99]
	v_fmac_f32_e32 v246, v214, v214
	v_fmac_f32_e32 v246, v215, v215
	v_fmac_f32_e32 v246, v216, v216
	v_fmac_f32_e32 v246, v217, v217
	v_cvt_pk_bf16_f32 v214, v214, v215
	v_cvt_pk_bf16_f32 v215, v216, v217
	global_store_dwordx2 v[242:243], v[214:215], off offset:96
	v_add_co_u32_e32 v242, vcc, 0x8000, v242
	s_nop 1
	v_addc_co_u32_e32 v243, vcc, 0, v243, vcc
	global_load_dwordx4 v[200:203], v[244:245], off offset:0
	global_load_dwordx4 v[204:207], v[244:245], off offset:64
	global_load_dwordx4 v[210:213], v[244:245], off offset:128
	global_load_dwordx4 v[214:217], v[244:245], off offset:192
	v_add_co_u32_e32 v244, vcc, 0x10000, v244
	s_nop 1
	v_addc_co_u32_e32 v245, vcc, 0, v245, vcc
	s_waitcnt vmcnt(8)
	v_pk_add_f32 v[218:219], v[218:219], v[4:5]
	v_pk_add_f32 v[220:221], v[220:221], v[6:7]
	v_fmac_f32_e32 v247, v218, v218
	v_fmac_f32_e32 v247, v219, v219
	v_fmac_f32_e32 v247, v220, v220
	v_fmac_f32_e32 v247, v221, v221
	v_cvt_pk_bf16_f32 v218, v218, v219
	v_cvt_pk_bf16_f32 v219, v220, v221
	global_store_dwordx2 v[242:243], v[218:219], off offset:0
	v_pk_add_f32 v[222:223], v[222:223], v[36:37]
	v_pk_add_f32 v[224:225], v[224:225], v[38:39]
	v_fmac_f32_e32 v247, v222, v222
	v_fmac_f32_e32 v247, v223, v223
	v_fmac_f32_e32 v247, v224, v224
	v_fmac_f32_e32 v247, v225, v225
	v_cvt_pk_bf16_f32 v222, v222, v223
	v_cvt_pk_bf16_f32 v223, v224, v225
	global_store_dwordx2 v[242:243], v[222:223], off offset:32
	v_pk_add_f32 v[226:227], v[226:227], v[68:69]
	v_pk_add_f32 v[228:229], v[228:229], v[70:71]
	v_fmac_f32_e32 v247, v226, v226
	v_fmac_f32_e32 v247, v227, v227
	v_fmac_f32_e32 v247, v228, v228
	v_fmac_f32_e32 v247, v229, v229
	v_cvt_pk_bf16_f32 v226, v226, v227
	v_cvt_pk_bf16_f32 v227, v228, v229
	global_store_dwordx2 v[242:243], v[226:227], off offset:64
	v_pk_add_f32 v[230:231], v[230:231], v[100:101]
	v_pk_add_f32 v[232:233], v[232:233], v[102:103]
	v_fmac_f32_e32 v247, v230, v230
	v_fmac_f32_e32 v247, v231, v231
	v_fmac_f32_e32 v247, v232, v232
	v_fmac_f32_e32 v247, v233, v233
	v_cvt_pk_bf16_f32 v230, v230, v231
	v_cvt_pk_bf16_f32 v231, v232, v233
	global_store_dwordx2 v[242:243], v[230:231], off offset:96
	v_add_co_u32_e32 v242, vcc, 0x8000, v242
	s_nop 1
	v_addc_co_u32_e32 v243, vcc, 0, v243, vcc
	global_load_dwordx4 v[218:221], v[244:245], off offset:0
	global_load_dwordx4 v[222:225], v[244:245], off offset:64
	global_load_dwordx4 v[226:229], v[244:245], off offset:128
	global_load_dwordx4 v[230:233], v[244:245], off offset:192
	v_add_co_u32_e32 v244, vcc, 0x10000, v244
	s_nop 1
	v_addc_co_u32_e32 v245, vcc, 0, v245, vcc
	s_waitcnt vmcnt(8)
	v_pk_add_f32 v[200:201], v[200:201], v[8:9]
	v_pk_add_f32 v[202:203], v[202:203], v[10:11]
	v_fmac_f32_e32 v248, v200, v200
	v_fmac_f32_e32 v248, v201, v201
	v_fmac_f32_e32 v248, v202, v202
	v_fmac_f32_e32 v248, v203, v203
	v_cvt_pk_bf16_f32 v200, v200, v201
	v_cvt_pk_bf16_f32 v201, v202, v203
	global_store_dwordx2 v[242:243], v[200:201], off offset:0
	v_pk_add_f32 v[204:205], v[204:205], v[40:41]
	v_pk_add_f32 v[206:207], v[206:207], v[42:43]
	v_fmac_f32_e32 v248, v204, v204
	v_fmac_f32_e32 v248, v205, v205
	v_fmac_f32_e32 v248, v206, v206
	v_fmac_f32_e32 v248, v207, v207
	v_cvt_pk_bf16_f32 v204, v204, v205
	v_cvt_pk_bf16_f32 v205, v206, v207
	global_store_dwordx2 v[242:243], v[204:205], off offset:32
	v_pk_add_f32 v[210:211], v[210:211], v[72:73]
	v_pk_add_f32 v[212:213], v[212:213], v[74:75]
	v_fmac_f32_e32 v248, v210, v210
	v_fmac_f32_e32 v248, v211, v211
	v_fmac_f32_e32 v248, v212, v212
	v_fmac_f32_e32 v248, v213, v213
	v_cvt_pk_bf16_f32 v210, v210, v211
	v_cvt_pk_bf16_f32 v211, v212, v213
	global_store_dwordx2 v[242:243], v[210:211], off offset:64
	v_pk_add_f32 v[214:215], v[214:215], v[104:105]
	v_pk_add_f32 v[216:217], v[216:217], v[106:107]
	v_fmac_f32_e32 v248, v214, v214
	v_fmac_f32_e32 v248, v215, v215
	v_fmac_f32_e32 v248, v216, v216
	v_fmac_f32_e32 v248, v217, v217
	v_cvt_pk_bf16_f32 v214, v214, v215
	v_cvt_pk_bf16_f32 v215, v216, v217
	global_store_dwordx2 v[242:243], v[214:215], off offset:96
	v_add_co_u32_e32 v242, vcc, 0x8000, v242
	s_nop 1
	v_addc_co_u32_e32 v243, vcc, 0, v243, vcc
	global_load_dwordx4 v[200:203], v[244:245], off offset:0
	global_load_dwordx4 v[204:207], v[244:245], off offset:64
	global_load_dwordx4 v[210:213], v[244:245], off offset:128
	global_load_dwordx4 v[214:217], v[244:245], off offset:192
	v_add_co_u32_e32 v244, vcc, 0x10000, v244
	s_nop 1
	v_addc_co_u32_e32 v245, vcc, 0, v245, vcc
	s_waitcnt vmcnt(8)
	v_pk_add_f32 v[218:219], v[218:219], v[12:13]
	v_pk_add_f32 v[220:221], v[220:221], v[14:15]
	v_fmac_f32_e32 v249, v218, v218
	v_fmac_f32_e32 v249, v219, v219
	v_fmac_f32_e32 v249, v220, v220
	v_fmac_f32_e32 v249, v221, v221
	v_cvt_pk_bf16_f32 v218, v218, v219
	v_cvt_pk_bf16_f32 v219, v220, v221
	global_store_dwordx2 v[242:243], v[218:219], off offset:0
	v_pk_add_f32 v[222:223], v[222:223], v[44:45]
	v_pk_add_f32 v[224:225], v[224:225], v[46:47]
	v_fmac_f32_e32 v249, v222, v222
	v_fmac_f32_e32 v249, v223, v223
	v_fmac_f32_e32 v249, v224, v224
	v_fmac_f32_e32 v249, v225, v225
	v_cvt_pk_bf16_f32 v222, v222, v223
	v_cvt_pk_bf16_f32 v223, v224, v225
	global_store_dwordx2 v[242:243], v[222:223], off offset:32
	v_pk_add_f32 v[226:227], v[226:227], v[76:77]
	v_pk_add_f32 v[228:229], v[228:229], v[78:79]
	v_fmac_f32_e32 v249, v226, v226
	v_fmac_f32_e32 v249, v227, v227
	v_fmac_f32_e32 v249, v228, v228
	v_fmac_f32_e32 v249, v229, v229
	v_cvt_pk_bf16_f32 v226, v226, v227
	v_cvt_pk_bf16_f32 v227, v228, v229
	global_store_dwordx2 v[242:243], v[226:227], off offset:64
	v_pk_add_f32 v[230:231], v[230:231], v[108:109]
	v_pk_add_f32 v[232:233], v[232:233], v[110:111]
	v_fmac_f32_e32 v249, v230, v230
	v_fmac_f32_e32 v249, v231, v231
	v_fmac_f32_e32 v249, v232, v232
	v_fmac_f32_e32 v249, v233, v233
	v_cvt_pk_bf16_f32 v230, v230, v231
	v_cvt_pk_bf16_f32 v231, v232, v233
	global_store_dwordx2 v[242:243], v[230:231], off offset:96
	v_add_co_u32_e32 v242, vcc, 0x8000, v242
	s_nop 1
	v_addc_co_u32_e32 v243, vcc, 0, v243, vcc
	global_load_dwordx4 v[218:221], v[244:245], off offset:0
	global_load_dwordx4 v[222:225], v[244:245], off offset:64
	global_load_dwordx4 v[226:229], v[244:245], off offset:128
	global_load_dwordx4 v[230:233], v[244:245], off offset:192
	v_add_co_u32_e32 v244, vcc, 0x10000, v244
	s_nop 1
	v_addc_co_u32_e32 v245, vcc, 0, v245, vcc
	s_waitcnt vmcnt(8)
	v_pk_add_f32 v[200:201], v[200:201], v[16:17]
	v_pk_add_f32 v[202:203], v[202:203], v[18:19]
	v_fmac_f32_e32 v250, v200, v200
	v_fmac_f32_e32 v250, v201, v201
	v_fmac_f32_e32 v250, v202, v202
	v_fmac_f32_e32 v250, v203, v203
	v_cvt_pk_bf16_f32 v200, v200, v201
	v_cvt_pk_bf16_f32 v201, v202, v203
	global_store_dwordx2 v[242:243], v[200:201], off offset:0
	v_pk_add_f32 v[204:205], v[204:205], v[48:49]
	v_pk_add_f32 v[206:207], v[206:207], v[50:51]
	v_fmac_f32_e32 v250, v204, v204
	v_fmac_f32_e32 v250, v205, v205
	v_fmac_f32_e32 v250, v206, v206
	v_fmac_f32_e32 v250, v207, v207
	v_cvt_pk_bf16_f32 v204, v204, v205
	v_cvt_pk_bf16_f32 v205, v206, v207
	global_store_dwordx2 v[242:243], v[204:205], off offset:32
	v_pk_add_f32 v[210:211], v[210:211], v[80:81]
	v_pk_add_f32 v[212:213], v[212:213], v[82:83]
	v_fmac_f32_e32 v250, v210, v210
	v_fmac_f32_e32 v250, v211, v211
	v_fmac_f32_e32 v250, v212, v212
	v_fmac_f32_e32 v250, v213, v213
	v_cvt_pk_bf16_f32 v210, v210, v211
	v_cvt_pk_bf16_f32 v211, v212, v213
	global_store_dwordx2 v[242:243], v[210:211], off offset:64
	v_pk_add_f32 v[214:215], v[214:215], v[112:113]
	v_pk_add_f32 v[216:217], v[216:217], v[114:115]
	v_fmac_f32_e32 v250, v214, v214
	v_fmac_f32_e32 v250, v215, v215
	v_fmac_f32_e32 v250, v216, v216
	v_fmac_f32_e32 v250, v217, v217
	v_cvt_pk_bf16_f32 v214, v214, v215
	v_cvt_pk_bf16_f32 v215, v216, v217
	global_store_dwordx2 v[242:243], v[214:215], off offset:96
	v_add_co_u32_e32 v242, vcc, 0x8000, v242
	s_nop 1
	v_addc_co_u32_e32 v243, vcc, 0, v243, vcc
	global_load_dwordx4 v[200:203], v[244:245], off offset:0
	global_load_dwordx4 v[204:207], v[244:245], off offset:64
	global_load_dwordx4 v[210:213], v[244:245], off offset:128
	global_load_dwordx4 v[214:217], v[244:245], off offset:192
	v_add_co_u32_e32 v244, vcc, 0x10000, v244
	s_nop 1
	v_addc_co_u32_e32 v245, vcc, 0, v245, vcc
	s_waitcnt vmcnt(8)
	v_pk_add_f32 v[218:219], v[218:219], v[20:21]
	v_pk_add_f32 v[220:221], v[220:221], v[22:23]
	v_fmac_f32_e32 v251, v218, v218
	v_fmac_f32_e32 v251, v219, v219
	v_fmac_f32_e32 v251, v220, v220
	v_fmac_f32_e32 v251, v221, v221
	v_cvt_pk_bf16_f32 v218, v218, v219
	v_cvt_pk_bf16_f32 v219, v220, v221
	global_store_dwordx2 v[242:243], v[218:219], off offset:0
	v_pk_add_f32 v[222:223], v[222:223], v[52:53]
	v_pk_add_f32 v[224:225], v[224:225], v[54:55]
	v_fmac_f32_e32 v251, v222, v222
	v_fmac_f32_e32 v251, v223, v223
	v_fmac_f32_e32 v251, v224, v224
	v_fmac_f32_e32 v251, v225, v225
	v_cvt_pk_bf16_f32 v222, v222, v223
	v_cvt_pk_bf16_f32 v223, v224, v225
	global_store_dwordx2 v[242:243], v[222:223], off offset:32
	v_pk_add_f32 v[226:227], v[226:227], v[84:85]
	v_pk_add_f32 v[228:229], v[228:229], v[86:87]
	v_fmac_f32_e32 v251, v226, v226
	v_fmac_f32_e32 v251, v227, v227
	v_fmac_f32_e32 v251, v228, v228
	v_fmac_f32_e32 v251, v229, v229
	v_cvt_pk_bf16_f32 v226, v226, v227
	v_cvt_pk_bf16_f32 v227, v228, v229
	global_store_dwordx2 v[242:243], v[226:227], off offset:64
	v_pk_add_f32 v[230:231], v[230:231], v[116:117]
	v_pk_add_f32 v[232:233], v[232:233], v[118:119]
	v_fmac_f32_e32 v251, v230, v230
	v_fmac_f32_e32 v251, v231, v231
	v_fmac_f32_e32 v251, v232, v232
	v_fmac_f32_e32 v251, v233, v233
	v_cvt_pk_bf16_f32 v230, v230, v231
	v_cvt_pk_bf16_f32 v231, v232, v233
	global_store_dwordx2 v[242:243], v[230:231], off offset:96
	v_add_co_u32_e32 v242, vcc, 0x8000, v242
	s_nop 1
	v_addc_co_u32_e32 v243, vcc, 0, v243, vcc
	global_load_dwordx4 v[218:221], v[244:245], off offset:0
	global_load_dwordx4 v[222:225], v[244:245], off offset:64
	global_load_dwordx4 v[226:229], v[244:245], off offset:128
	global_load_dwordx4 v[230:233], v[244:245], off offset:192
	v_add_co_u32_e32 v244, vcc, 0x10000, v244
	s_nop 1
	v_addc_co_u32_e32 v245, vcc, 0, v245, vcc
	s_waitcnt vmcnt(8)
	v_pk_add_f32 v[200:201], v[200:201], v[24:25]
	v_pk_add_f32 v[202:203], v[202:203], v[26:27]
	v_fmac_f32_e32 v252, v200, v200
	v_fmac_f32_e32 v252, v201, v201
	v_fmac_f32_e32 v252, v202, v202
	v_fmac_f32_e32 v252, v203, v203
	v_cvt_pk_bf16_f32 v200, v200, v201
	v_cvt_pk_bf16_f32 v201, v202, v203
	global_store_dwordx2 v[242:243], v[200:201], off offset:0
	v_pk_add_f32 v[204:205], v[204:205], v[56:57]
	v_pk_add_f32 v[206:207], v[206:207], v[58:59]
	v_fmac_f32_e32 v252, v204, v204
	v_fmac_f32_e32 v252, v205, v205
	v_fmac_f32_e32 v252, v206, v206
	v_fmac_f32_e32 v252, v207, v207
	v_cvt_pk_bf16_f32 v204, v204, v205
	v_cvt_pk_bf16_f32 v205, v206, v207
	global_store_dwordx2 v[242:243], v[204:205], off offset:32
	v_pk_add_f32 v[210:211], v[210:211], v[88:89]
	v_pk_add_f32 v[212:213], v[212:213], v[90:91]
	v_fmac_f32_e32 v252, v210, v210
	v_fmac_f32_e32 v252, v211, v211
	v_fmac_f32_e32 v252, v212, v212
	v_fmac_f32_e32 v252, v213, v213
	v_cvt_pk_bf16_f32 v210, v210, v211
	v_cvt_pk_bf16_f32 v211, v212, v213
	global_store_dwordx2 v[242:243], v[210:211], off offset:64
	v_pk_add_f32 v[214:215], v[214:215], v[120:121]
	v_pk_add_f32 v[216:217], v[216:217], v[122:123]
	v_fmac_f32_e32 v252, v214, v214
	v_fmac_f32_e32 v252, v215, v215
	v_fmac_f32_e32 v252, v216, v216
	v_fmac_f32_e32 v252, v217, v217
	v_cvt_pk_bf16_f32 v214, v214, v215
	v_cvt_pk_bf16_f32 v215, v216, v217
	global_store_dwordx2 v[242:243], v[214:215], off offset:96
	v_add_co_u32_e32 v242, vcc, 0x8000, v242
	s_nop 1
	v_addc_co_u32_e32 v243, vcc, 0, v243, vcc
	s_waitcnt vmcnt(4)
	v_pk_add_f32 v[218:219], v[218:219], v[28:29]
	v_pk_add_f32 v[220:221], v[220:221], v[30:31]
	v_fmac_f32_e32 v253, v218, v218
	v_fmac_f32_e32 v253, v219, v219
	v_fmac_f32_e32 v253, v220, v220
	v_fmac_f32_e32 v253, v221, v221
	v_cvt_pk_bf16_f32 v218, v218, v219
	v_cvt_pk_bf16_f32 v219, v220, v221
	global_store_dwordx2 v[242:243], v[218:219], off offset:0
	v_pk_add_f32 v[222:223], v[222:223], v[60:61]
	v_pk_add_f32 v[224:225], v[224:225], v[62:63]
	v_fmac_f32_e32 v253, v222, v222
	v_fmac_f32_e32 v253, v223, v223
	v_fmac_f32_e32 v253, v224, v224
	v_fmac_f32_e32 v253, v225, v225
	v_cvt_pk_bf16_f32 v222, v222, v223
	v_cvt_pk_bf16_f32 v223, v224, v225
	global_store_dwordx2 v[242:243], v[222:223], off offset:32
	v_pk_add_f32 v[226:227], v[226:227], v[92:93]
	v_pk_add_f32 v[228:229], v[228:229], v[94:95]
	v_fmac_f32_e32 v253, v226, v226
	v_fmac_f32_e32 v253, v227, v227
	v_fmac_f32_e32 v253, v228, v228
	v_fmac_f32_e32 v253, v229, v229
	v_cvt_pk_bf16_f32 v226, v226, v227
	v_cvt_pk_bf16_f32 v227, v228, v229
	global_store_dwordx2 v[242:243], v[226:227], off offset:64
	v_pk_add_f32 v[230:231], v[230:231], v[124:125]
	v_pk_add_f32 v[232:233], v[232:233], v[126:127]
	v_fmac_f32_e32 v253, v230, v230
	v_fmac_f32_e32 v253, v231, v231
	v_fmac_f32_e32 v253, v232, v232
	v_fmac_f32_e32 v253, v233, v233
	v_cvt_pk_bf16_f32 v230, v230, v231
	v_cvt_pk_bf16_f32 v231, v232, v233
	global_store_dwordx2 v[242:243], v[230:231], off offset:96
	v_add_co_u32_e32 v242, vcc, 0x8000, v242
	s_nop 1
	v_addc_co_u32_e32 v243, vcc, 0, v243, vcc
	v_and_b32_e32 v200, 63, v208
	v_and_b32_e32 v205, 15, v200
	v_lshrrev_b32_e32 v206, 4, v200
	v_and_b32_e32 v207, 7, v205
	v_xor_b32_e32 v207, v207, v206
	v_lshlrev_b32_e32 v207, 4, v207
	v_lshl_add_u32 v242, v205, 7, v207
	v_xor_b32_e32 v243, 64, v242
	s_add_i32 s21, s21, 1
	s_cmp_lt_u32 s21, 4
	s_cbranch_scc1 .Lg2_chunk
	s_waitcnt vmcnt(0)
	v_and_b32_e32 v200, 63, v208
	v_xor_b32_e32 v201, 16, v200
	v_lshlrev_b32_e32 v201, 2, v201
	v_xor_b32_e32 v202, 32, v200
	v_lshlrev_b32_e32 v202, 2, v202
	v_and_b32_e32 v203, 15, v200
	v_lshlrev_b32_e32 v203, 2, v203
	v_add_u32_e32 v203, 0x12400, v203
	ds_bpermute_b32 v204, v201, v246
	s_waitcnt lgkmcnt(0)
	v_add_f32_e32 v246, v246, v204
	ds_bpermute_b32 v204, v202, v246
	s_waitcnt lgkmcnt(0)
	v_add_f32_e32 v246, v246, v204
	ds_bpermute_b32 v204, v201, v247
	s_waitcnt lgkmcnt(0)
	v_add_f32_e32 v247, v247, v204
	ds_bpermute_b32 v204, v202, v247
	s_waitcnt lgkmcnt(0)
	v_add_f32_e32 v247, v247, v204
	ds_bpermute_b32 v204, v201, v248
	s_waitcnt lgkmcnt(0)
	v_add_f32_e32 v248, v248, v204
	ds_bpermute_b32 v204, v202, v248
	s_waitcnt lgkmcnt(0)
	v_add_f32_e32 v248, v248, v204
	ds_bpermute_b32 v204, v201, v249
	s_waitcnt lgkmcnt(0)
	v_add_f32_e32 v249, v249, v204
	ds_bpermute_b32 v204, v202, v249
	s_waitcnt lgkmcnt(0)
	v_add_f32_e32 v249, v249, v204
	ds_bpermute_b32 v204, v201, v250
	s_waitcnt lgkmcnt(0)
	v_add_f32_e32 v250, v250, v204
	ds_bpermute_b32 v204, v202, v250
	s_waitcnt lgkmcnt(0)
	v_add_f32_e32 v250, v250, v204
	ds_bpermute_b32 v204, v201, v251
	s_waitcnt lgkmcnt(0)
	v_add_f32_e32 v251, v251, v204
	ds_bpermute_b32 v204, v202, v251
	s_waitcnt lgkmcnt(0)
	v_add_f32_e32 v251, v251, v204
	ds_bpermute_b32 v204, v201, v252
	s_waitcnt lgkmcnt(0)
	v_add_f32_e32 v252, v252, v204
	ds_bpermute_b32 v204, v202, v252
	s_waitcnt lgkmcnt(0)
	v_add_f32_e32 v252, v252, v204
	ds_bpermute_b32 v204, v201, v253
	s_waitcnt lgkmcnt(0)
	v_add_f32_e32 v253, v253, v204
	ds_bpermute_b32 v204, v202, v253
	s_waitcnt lgkmcnt(0)
	v_add_f32_e32 v253, v253, v204
	s_mov_b64 s[24:25], exec
	s_mov_b64 exec, 0xffff
	ds_add_f32 v203, v246 offset:0
	ds_add_f32 v203, v247 offset:64
	ds_add_f32 v203, v248 offset:128
	ds_add_f32 v203, v249 offset:192
	ds_add_f32 v203, v250 offset:256
	ds_add_f32 v203, v251 offset:320
	ds_add_f32 v203, v252 offset:384
	ds_add_f32 v203, v253 offset:448
	s_mov_b64 exec, s[24:25]

